# attention-B: next-step K/V tiles staged into LDS between the two sub-tiles instead of right before the step barrier (on top of v81)
# speedup vs baseline: 1.0218x; 1.0021x over previous
.LBB0_598:
	s_andn2_b64 vcc, exec, s[14:15]
	s_cbranch_vccnz .Lmy_nowr
	s_xor_b32 s16, s97, 1
	s_mulk_i32 s16, 0x4800
	v_add_u32_e32 v0, s16, v242
	s_bitcmp0_b32 s32, 0
	s_cbranch_scc1 .Lkvb_w0
	s_waitcnt vmcnt(4)
	s_branch .Lkvb_w1

.Lkvb_st_odd:
	ds_write_b128 v0, v[100:103]
	ds_write_b128 v0, v[104:107] offset:9216
	ds_write_b128 v0, v[108:111] offset:36864
	ds_write_b128 v0, v[112:115] offset:46080
.Lmy_nowr:
	s_add_i32 s16, s41, 1
	s_cmp_lt_i32 s16, s37
	s_cselect_b64 s[16:17], -1, 0
	s_cmp_ge_i32 s41, s36
	s_cselect_b64 s[64:65], -1, 0
	s_or_b64 s[16:17], s[64:65], s[16:17]
	s_and_b64 vcc, exec, s[16:17]
	s_cbranch_vccnz .LBB0_612
	ds_read2_b64 v[180:183], v252 offset0:64 offset1:96
	s_bitcmp1_b32 s32, 1
	s_cbranch_scc1 .Lmy_k2skip
	ds_read_b128 v[172:175], v234 offset:9216
	ds_read_b128 v[160:163], v234 offset:9248
	ds_read_b128 v[176:179], v234 offset:13824
	ds_read_b128 v[164:167], v234 offset:13856
	ds_read_b128 v[156:159], v234 offset:9280
	ds_read_b128 v[152:155], v234 offset:9312
	ds_read_b128 v[168:171], v234 offset:13888

.LBB0_612:
	s_andn2_b64 vcc, exec, s[14:15]
	s_cbranch_vccnz .LBB0_581
	s_branch .LBB0_581
